# k10 plus counted lgkmcnt waits at first consumer (instead of lgkmcnt(0) per group) in the mixer-A PV transpose-read block
# speedup vs baseline: 1.0004x; 1.0004x over previous
; #define SBAR() __builtin_amdgcn_sched_barrier(0)
; template <int D0> __device__ __forceinline__ void pv_one(f32x16& od, int vb, bf16x8 pa0, bf16x8 pa1, bf16x8 pa2, bf16x8 pa3) {
;     const s16x4 l0 = tr_read<v_rd_off(D0, 0, 0)>(vb), h0 = tr_read<v_rd_off(D0, 0, 1)>(vb), l1 = tr_read<v_rd_off(D0, 1, 0)>(vb), h1 = tr_read<v_rd_off(D0, 1, 1)>(vb);
;     const s16x4 l2 = tr_read<v_rd_off(D0, 2, 0)>(vb), h2 = tr_read<v_rd_off(D0, 2, 1)>(vb), l3 = tr_read<v_rd_off(D0, 3, 0)>(vb), h3 = tr_read<v_rd_off(D0, 3, 1)>(vb);
;     asm volatile("s_waitcnt lgkmcnt(0)" ::: "memory"); SBAR();
;     ...
;     od = __builtin_amdgcn_mfma_f32_32x32x16_bf16(pa0, PK(l0, h0), od, 0, 0, 0);
;     od = __builtin_amdgcn_mfma_f32_32x32x16_bf16(pa1, PK(l1, h1), od, 0, 0, 0);
;     od = __builtin_amdgcn_mfma_f32_32x32x16_bf16(pa2, PK(l2, h2), od, 0, 0, 0);
;     od = __builtin_amdgcn_mfma_f32_32x32x16_bf16(pa3, PK(l3, h3), od, 0, 0, 0);
;     ...
; }
; template <int MODE>
; __device__ __forceinline__ void flash_core(const bf16_t* __restrict__ Qg, const bf16_t* __restrict__ Kg, const bf16_t* __restrict__ Vg,
;                                            int jlo, int jhi, int wlo, int whi, int qpos0, float slope2, char* lds, f32x16 (&o)[4], float& l_out) {
;     ...
;             bf16x8 pa0, pa1, pa2, pa3;
;     ...
;             PK4(p0, 0, pa0); PK4(p0, 8, pa1); PK4(p1, 0, pa2); PK4(p1, 8, pa3);
;     ...
;             pv_one<0>(o[0], vb, pa0, pa1, pa2, pa3); pv_one<1>(o[1], vb, pa0, pa1, pa2, pa3);
;             pv_one<2>(o[2], vb, pa0, pa1, pa2, pa3); pv_one<3>(o[3], vb, pa0, pa1, pa2, pa3);
.LBB0_411:
	v_add_u32_e32 v107, s30, v200
	v_cvt_pk_bf16_f32 v80, v80, v81
	v_cvt_pk_bf16_f32 v81, v82, v83
	v_cvt_pk_bf16_f32 v82, v84, v85
	v_cvt_pk_bf16_f32 v85, v91, v92
	v_cvt_pk_bf16_f32 v91, v6, v7
	ds_read_b64_tr_b16 v[6:7], v107 offset:0
	v_cvt_pk_bf16_f32 v83, v86, v89
	v_cvt_pk_bf16_f32 v86, v93, v94
	v_cvt_pk_bf16_f32 v93, v2, v11
	v_cvt_pk_bf16_f32 v2, v3, v8
	v_cvt_pk_bf16_f32 v3, v9, v14
	ds_read_b64_tr_b16 v[8:9], v107 offset:0x800
	v_cvt_pk_bf16_f32 v84, v87, v90
	v_cvt_pk_bf16_f32 v90, v0, v10
	ds_read_b64_tr_b16 v[10:11], v107 offset:0x1000
	v_cvt_pk_bf16_f32 v92, v4, v5
	v_cvt_pk_bf16_f32 v4, v12, v13
	ds_read_b64_tr_b16 v[12:13], v107 offset:0x1800
	v_add_f32_e32 v106, v98, v99
	v_cvt_pk_bf16_f32 v87, v95, v96
	ds_read_b64_tr_b16 v[94:95], v107 offset:0x2000
	v_fmac_f32_e32 v106, v203, v97
	ds_read_b64_tr_b16 v[96:97], v107 offset:0x2800
	ds_read_b64_tr_b16 v[98:99], v107 offset:0x3000
	ds_read_b64_tr_b16 v[100:101], v107 offset:0x3800
	s_waitcnt lgkmcnt(0)
	v_cvt_pk_bf16_f32 v5, v15, v88
	v_permlane32_swap_b32_e32 v80, v82
	v_permlane32_swap_b32_e32 v81, v83
	v_permlane32_swap_b32_e32 v84, v86
	v_permlane32_swap_b32_e32 v85, v87
	v_permlane32_swap_b32_e32 v90, v92
	v_permlane32_swap_b32_e32 v91, v93
	v_permlane32_swap_b32_e32 v2, v4
	v_permlane32_swap_b32_e32 v3, v5
	v_mfma_f32_32x32x16_bf16 v[64:79], v[80:83], v[6:9], v[64:79]
	ds_read_b64_tr_b16 v[6:7], v107 offset:0x200
	ds_read_b64_tr_b16 v[8:9], v107 offset:0xa00
	v_mfma_f32_32x32x16_bf16 v[64:79], v[84:87], v[10:13], v[64:79]
	ds_read_b64_tr_b16 v[10:11], v107 offset:0x1200
	ds_read_b64_tr_b16 v[12:13], v107 offset:0x1a00
	v_mfma_f32_32x32x16_bf16 v[64:79], v[90:93], v[94:97], v[64:79]
	ds_read_b64_tr_b16 v[94:95], v107 offset:0x2200
	ds_read_b64_tr_b16 v[96:97], v107 offset:0x2a00
	ds_read_b64_tr_b16 v[102:103], v107 offset:0x3200
	ds_read_b64_tr_b16 v[104:105], v107 offset:0x3a00
	v_mfma_f32_32x32x16_bf16 v[64:79], v[2:5], v[98:101], v[64:79]
	s_waitcnt lgkmcnt(6)
	v_mfma_f32_32x32x16_bf16 v[48:63], v[80:83], v[6:9], v[48:63]
	ds_read_b64_tr_b16 v[6:7], v107 offset:0x400
	ds_read_b64_tr_b16 v[8:9], v107 offset:0xc00
	s_waitcnt lgkmcnt(6)
	v_mfma_f32_32x32x16_bf16 v[48:63], v[84:87], v[10:13], v[48:63]
	ds_read_b64_tr_b16 v[10:11], v107 offset:0x1400
	ds_read_b64_tr_b16 v[12:13], v107 offset:0x1c00
	s_waitcnt lgkmcnt(6)
	v_mfma_f32_32x32x16_bf16 v[48:63], v[90:93], v[94:97], v[48:63]
	ds_read_b64_tr_b16 v[94:95], v107 offset:0x2400
	ds_read_b64_tr_b16 v[96:97], v107 offset:0x2c00
	ds_read_b64_tr_b16 v[98:99], v107 offset:0x3400
	ds_read_b64_tr_b16 v[100:101], v107 offset:0x3c00
	s_waitcnt lgkmcnt(8)
	v_mfma_f32_32x32x16_bf16 v[48:63], v[2:5], v[102:105], v[48:63]
	s_waitcnt lgkmcnt(6)
	v_mfma_f32_32x32x16_bf16 v[32:47], v[80:83], v[6:9], v[32:47]
	ds_read_b64_tr_b16 v[6:7], v107 offset:0x600
	ds_read_b64_tr_b16 v[8:9], v107 offset:0xe00
	s_waitcnt lgkmcnt(6)
	v_mfma_f32_32x32x16_bf16 v[32:47], v[84:87], v[10:13], v[32:47]
	ds_read_b64_tr_b16 v[10:11], v107 offset:0x1600
	ds_read_b64_tr_b16 v[12:13], v107 offset:0x1e00
	s_waitcnt lgkmcnt(6)
	v_mfma_f32_32x32x16_bf16 v[32:47], v[90:93], v[94:97], v[32:47]
	ds_read_b64_tr_b16 v[94:95], v107 offset:0x2600
	ds_read_b64_tr_b16 v[96:97], v107 offset:0x2e00
	ds_read_b64_tr_b16 v[102:103], v107 offset:0x3600
	ds_read_b64_tr_b16 v[104:105], v107 offset:0x3e00
	s_waitcnt lgkmcnt(8)
	v_mfma_f32_32x32x16_bf16 v[32:47], v[2:5], v[98:101], v[32:47]
	s_waitcnt lgkmcnt(6)
	v_mfma_f32_32x32x16_bf16 v[16:31], v[80:83], v[6:9], v[16:31]
	v_mov_b32_e32 v203, v106
	s_waitcnt lgkmcnt(4)
	v_mfma_f32_32x32x16_bf16 v[16:31], v[84:87], v[10:13], v[16:31]
	s_waitcnt lgkmcnt(2)
	v_mfma_f32_32x32x16_bf16 v[16:31], v[90:93], v[94:97], v[16:31]
	s_waitcnt lgkmcnt(0)
	v_mfma_f32_32x32x16_bf16 v[16:31], v[2:5], v[102:105], v[16:31]
